# v73 + ALiBi bias through the QK^T C operand on uniform-sign tiles (34 VALU instead of 64 per step), QK^T order p0 x4 then p1 x4
# speedup vs baseline: 1.0326x; 1.0182x over previous
; __device__ __forceinline__ void attn_unit_pp(int b, int h, int qb, int par, const bf16_t* __restrict__ QBp, const bf16_t* __restrict__ KBp, const bf16_t* __restrict__ VBp, ...
;     ...
;   const int tid = tid_, wid = tid >> 6, lane = tid & 63, r32 = lane & 31, hi = lane >> 5, w4 = wid & 3, t256 = tid & 255;
;   const int g = __builtin_amdgcn_readfirstlane(tid >> 8);
;   const long rowbase = (long)b * SEQ; const int q0 = qb * 128;
;   const size_t hoff = HEADMAJOR ? (size_t)(b * 8 + h) * SEQ * 128 : (size_t)b * SEQ * 1024 + h * 128;
;   const bf16_t* Kh = KBp + hoff; const bf16_t* Vh = VBp + hoff;
;   char* V_lds = lds; char* K_lds = lds + 2 * SHM_V;
;   float* wsf = (float*)(lds + 2 * SHM_V + 2 * SHM_K) + wid * 64; float* li_l = wsf; float* al_l = wsf + 32;
;   const float nslope = -exp2f(-(float)(h + 1)) * 1.4426950408889634f;
;   const bf16_t* Qw = QBp + hoff + (size_t)(q0 + w4 * QBLK + r32) * LD + g * 64 + hi * 8;
;   bf16x8 qr[4];
; #pragma unroll
;   for (int d0 = 0; d0 < 4; ++d0) qr[d0] = ld8(Qw + d0 * 16);
.LBB0_339:
	s_lshl_b32 s0, s82, 1
	s_ashr_i32 s2, s83, 7
	s_lshr_b32 s3, s83, 4
	s_add_i32 s6, s82, s9
	s_add_i32 s10, s0, s35
	s_add_i32 s11, s82, s40
	s_and_b64 s[0:1], s[4:5], exec
	s_cselect_b32 s0, s11, s83
	s_cselect_b32 s1, s6, s3
	s_cselect_b32 s10, s10, s2
	s_and_b32 s6, s1, 7
	s_and_b32 s22, s0, 15
	v_mov_b32_e32 v4, v174
	s_lshl_b32 s0, s10, 3
	s_or_b32 s16, s0, s6
	v_ashrrev_i32_e32 v3, 6, v4
	v_and_b32_e32 v184, 3, v3
	v_readfirstlane_b32 s2, v4
	s_ashr_i32 s17, s16, 31
	v_and_b32_e32 v179, 31, v4
	s_ashr_i32 s38, s2, 8
	s_bfe_u32 s99, s2, 0x20006
	s_lshl2_add_u32 s99, s22, s99
	s_lshl_b32 s84, s22, 7
	s_lshl_b64 s[0:1], s[16:17], 19
	v_lshlrev_b32_e32 v185, 5, v184
	s_add_u32 s0, s18, s0
	v_or3_b32 v5, v179, s84, v185
	s_addc_u32 s1, s19, s1
	v_lshlrev_b32_e32 v0, 8, v5
	s_lshl_b32 s46, s38, 6
	v_bfe_u32 v6, v4, 5, 1
	v_lshl_add_u64 v[8:9], s[0:1], 0, v[0:1]
	s_ashr_i32 s47, s46, 31
	v_lshl_add_u64 v[8:9], s[46:47], 1, v[8:9]
	v_lshlrev_b32_e32 v0, 4, v6
	v_lshl_add_u64 v[8:9], v[8:9], 0, v[0:1]
	global_load_dwordx4 v[130:133], v[8:9], off
	global_load_dwordx4 v[134:137], v[8:9], off offset:32
	global_load_dwordx4 v[138:141], v[8:9], off offset:64
	global_load_dwordx4 v[142:145], v[8:9], off offset:96
	v_lshlrev_b32_e32 v8, 3, v4
	v_and_b32_e32 v2, 0x78, v8
	s_cmpk_lt_u32 s2, 0x100
	v_lshlrev_b32_e32 v2, 1, v2
	v_and_b32_e32 v9, 0x70, v4
	v_bfe_u32 v7, v4, 4, 4
	s_cselect_b64 s[12:13], -1, 0
	s_cmpk_gt_u32 s2, 0xff
	v_bitop3_b32 v10, v2, s48, v9 bitop3:0xde
	s_cselect_b64 s[2:3], -1, 0
	s_and_b64 vcc, exec, s[12:13]
	v_lshl_or_b32 v16, v7, 8, v10
	s_mov_b64 s[0:1], -1
	s_cbranch_vccnz .LBB0_341
	v_lshl_or_b32 v17, v7, 8, v10
	s_mov_b64 s[0:1], 0

; __device__ __forceinline__ void qkt_c(f32x16& p0, f32x16& p1, const char* Ks, const bf16x8* qr, const f32x16& negm, int r32, int hi) {
; #pragma unroll
;   for (int d0 = 0; d0 < 4; ++d0) { const int cb = (d0 * 16 + hi * 8) * 2;
;     bf16x8 b0 = *reinterpret_cast<const bf16x8*>(Ks + KSWZ(r32, cb));
;     bf16x8 b1 = *reinterpret_cast<const bf16x8*>(Ks + KSWZ(32 + r32, cb));
;     if (d0 == 0) { p0 = __builtin_amdgcn_mfma_f32_32x32x16_bf16(b0, qr[0], negm, 0, 0, 0); p1 = __builtin_amdgcn_mfma_f32_32x32x16_bf16(b1, qr[0], negm, 0, 0, 0); }
;     else { p0 = __builtin_amdgcn_mfma_f32_32x32x16_bf16(b0, qr[d0], p0, 0, 0, 0); p1 = __builtin_amdgcn_mfma_f32_32x32x16_bf16(b1, qr[d0], p1, 0, 0, 0); } }
; }
; template <int R> __device__ __forceinline__ void bias_r(f32x16& p0, f32x16& p1, float dq, float nslope) {
;   constexpr int C0 = (R & 3) + 8 * (R >> 2);
;   float x0, x1, a0 = p0[R], a1 = p1[R];
;   asm("v_sub_f32_e32 %0, %1, %2" : "=v"(x0) : "n"(__builtin_bit_cast(int, (float)C0)), "v"(dq));
;   asm("v_sub_f32_e32 %0, %1, %2" : "=v"(x1) : "n"(__builtin_bit_cast(int, (float)(C0 + 32))), "v"(dq));
;   asm("v_fma_f32 %0, %1, |%2|, %0" : "+v"(a0) : "v"(nslope), "v"(x0));
;   asm("v_fma_f32 %0, %1, |%2|, %0" : "+v"(a1) : "v"(nslope), "v"(x1));
;   p0[R] = a0; p1[R] = a1;
;   if constexpr (R < 15) bias_r<R + 1>(p0, p1, dq, nslope);
; }
.LBB0_364:
	ds_read_b128 v[114:117], v195 offset:32768
	ds_read_b128 v[212:215], v196 offset:32768
	ds_read_b128 v[216:219], v197 offset:32768
	s_and_b64 vcc, exec, s[14:15]
	s_add_i32 s72, s22, s46
	s_cmp_lt_i32 s46, s23
	s_cselect_b32 s14, s72, s39
	s_lshl_b32 s74, s14, 1
	s_sub_i32 s74, s74, s99
	s_add_i32 s75, s74, 1
	s_lshl_b32 s14, s14, 6
	v_cvt_f32_i32_e32 v0, s14
	v_sub_f32_e32 v0, v192, v0
	s_cmp_lt_u32 s75, 2
	s_cbranch_scc1 .Lbc_mix_0
	s_and_b32 s75, s74, 0x80000000
	v_xor_b32_e32 v14, s75, v81
	v_fma_f32 v15, -v14, v0, v82
	v_fmamk_f32 v240, v14, 0x00000000, v15
	v_fmamk_f32 v241, v14, 0x3f800000, v15
	v_fmamk_f32 v242, v14, 0x40000000, v15
	v_fmamk_f32 v243, v14, 0x40400000, v15
	v_fmamk_f32 v244, v14, 0x41000000, v15
	v_fmamk_f32 v245, v14, 0x41100000, v15
	v_fmamk_f32 v246, v14, 0x41200000, v15
	v_fmamk_f32 v247, v14, 0x41300000, v15
	v_fmamk_f32 v248, v14, 0x41800000, v15
	v_fmamk_f32 v249, v14, 0x41880000, v15
	v_fmamk_f32 v250, v14, 0x41900000, v15
	v_fmamk_f32 v251, v14, 0x41980000, v15
	v_fmamk_f32 v252, v14, 0x41c00000, v15
	v_fmamk_f32 v253, v14, 0x41c80000, v15
	v_fmamk_f32 v254, v14, 0x41d00000, v15
	v_fmamk_f32 v255, v14, 0x41d80000, v15
	s_nop 1
	s_waitcnt lgkmcnt(2)
	v_mfma_f32_32x32x16_bf16 v[98:113], v[114:117], v[130:133], v[240:255]
	ds_read_b128 v[220:223], v198 offset:32768
	s_waitcnt lgkmcnt(2)
	v_mfma_f32_32x32x16_bf16 v[98:113], v[212:215], v[134:137], v[98:113]
	ds_read_b128 v[212:215], v195 offset:40960
	s_waitcnt lgkmcnt(2)
	v_mfma_f32_32x32x16_bf16 v[98:113], v[216:219], v[138:141], v[98:113]
	ds_read_b128 v[216:219], v196 offset:40960
	v_fmamk_f32 v240, v14, 0x42000000, v15
	v_fmamk_f32 v241, v14, 0x42040000, v15
	v_fmamk_f32 v242, v14, 0x42080000, v15
	v_fmamk_f32 v243, v14, 0x420c0000, v15
	v_fmamk_f32 v244, v14, 0x42200000, v15
	v_fmamk_f32 v245, v14, 0x42240000, v15
	v_fmamk_f32 v246, v14, 0x42280000, v15
	v_fmamk_f32 v247, v14, 0x422c0000, v15
	s_waitcnt lgkmcnt(2)
	v_mfma_f32_32x32x16_bf16 v[98:113], v[220:223], v[142:145], v[98:113]
	v_fmamk_f32 v248, v14, 0x42400000, v15
	v_fmamk_f32 v249, v14, 0x42440000, v15
	v_fmamk_f32 v250, v14, 0x42480000, v15
	v_fmamk_f32 v251, v14, 0x424c0000, v15
	v_fmamk_f32 v252, v14, 0x42600000, v15
	v_fmamk_f32 v253, v14, 0x42640000, v15
	v_fmamk_f32 v254, v14, 0x42680000, v15
	v_fmamk_f32 v255, v14, 0x426c0000, v15
	ds_read_b128 v[220:223], v197 offset:40960
	s_waitcnt lgkmcnt(2)
	v_mfma_f32_32x32x16_bf16 v[114:129], v[212:215], v[130:133], v[240:255]
	ds_read_b128 v[212:215], v198 offset:40960
	s_waitcnt lgkmcnt(2)
	v_mfma_f32_32x32x16_bf16 v[114:129], v[216:219], v[134:137], v[114:129]
	s_cbranch_vccnz .Lbc_tail_u_0
	ds_read_b64_tr_b16 v[204:205], v194 offset:0
	ds_read_b64_tr_b16 v[206:207], v194 offset:0x800
	ds_read_b64_tr_b16 v[208:209], v194 offset:0x1000
	ds_read_b64_tr_b16 v[210:211], v194 offset:0x1800
	s_waitcnt lgkmcnt(5)
	v_mfma_f32_32x32x16_bf16 v[114:129], v[220:223], v[138:141], v[114:129]
	s_waitcnt lgkmcnt(4)
	v_mfma_f32_32x32x16_bf16 v[114:129], v[212:215], v[142:145], v[114:129]
	ds_read_b64_tr_b16 v[212:213], v194 offset:0x2000
	ds_read_b64_tr_b16 v[214:215], v194 offset:0x2800
	ds_read_b64_tr_b16 v[216:217], v194 offset:0x3000
	ds_read_b64_tr_b16 v[218:219], v194 offset:0x3800
	s_waitcnt lgkmcnt(6)
	v_mfma_f32_32x32x16_bf16 v[64:79], v[2:5], v[204:207], v[64:79]
	ds_read_b64_tr_b16 v[204:205], v194 offset:0x200
	ds_read_b64_tr_b16 v[206:207], v194 offset:0xa00
	s_waitcnt lgkmcnt(6)
	v_mfma_f32_32x32x16_bf16 v[64:79], v[6:9], v[208:211], v[64:79]
	ds_read_b64_tr_b16 v[208:209], v194 offset:0x1200
	ds_read_b64_tr_b16 v[210:211], v194 offset:0x1a00
	s_waitcnt lgkmcnt(6)
	v_mfma_f32_32x32x16_bf16 v[64:79], v[10:13], v[212:215], v[64:79]
	ds_read_b64_tr_b16 v[212:213], v194 offset:0x2200
	ds_read_b64_tr_b16 v[214:215], v194 offset:0x2a00
	ds_read_b64_tr_b16 v[220:221], v194 offset:0x3200
	ds_read_b64_tr_b16 v[222:223], v194 offset:0x3a00
	s_waitcnt lgkmcnt(8)
	v_mfma_f32_32x32x16_bf16 v[64:79], v[162:165], v[216:219], v[64:79]
	s_waitcnt lgkmcnt(6)
	v_mfma_f32_32x32x16_bf16 v[48:63], v[2:5], v[204:207], v[48:63]
	ds_read_b64_tr_b16 v[204:205], v194 offset:0x400
	ds_read_b64_tr_b16 v[206:207], v194 offset:0xc00
	s_waitcnt lgkmcnt(6)
	v_mfma_f32_32x32x16_bf16 v[48:63], v[6:9], v[208:211], v[48:63]
	ds_read_b64_tr_b16 v[208:209], v194 offset:0x1400
	ds_read_b64_tr_b16 v[210:211], v194 offset:0x1c00
	s_waitcnt lgkmcnt(6)
	v_mfma_f32_32x32x16_bf16 v[48:63], v[10:13], v[212:215], v[48:63]
	ds_read_b64_tr_b16 v[212:213], v194 offset:0x2400
	ds_read_b64_tr_b16 v[214:215], v194 offset:0x2c00
	ds_read_b64_tr_b16 v[216:217], v194 offset:0x3400
	ds_read_b64_tr_b16 v[218:219], v194 offset:0x3c00
	s_waitcnt lgkmcnt(8)
	v_mfma_f32_32x32x16_bf16 v[48:63], v[162:165], v[220:223], v[48:63]
	s_waitcnt lgkmcnt(6)
	v_mfma_f32_32x32x16_bf16 v[32:47], v[2:5], v[204:207], v[32:47]
	ds_read_b64_tr_b16 v[204:205], v194 offset:0x600
	ds_read_b64_tr_b16 v[206:207], v194 offset:0xe00
	s_waitcnt lgkmcnt(6)
	v_mfma_f32_32x32x16_bf16 v[32:47], v[6:9], v[208:211], v[32:47]
	ds_read_b64_tr_b16 v[208:209], v194 offset:0x1600
	ds_read_b64_tr_b16 v[210:211], v194 offset:0x1e00
	s_waitcnt lgkmcnt(6)
	v_mfma_f32_32x32x16_bf16 v[32:47], v[10:13], v[212:215], v[32:47]
	ds_read_b64_tr_b16 v[212:213], v194 offset:0x2600
	ds_read_b64_tr_b16 v[214:215], v194 offset:0x2e00
	ds_read_b64_tr_b16 v[220:221], v194 offset:0x3600
	ds_read_b64_tr_b16 v[222:223], v194 offset:0x3e00
	s_waitcnt lgkmcnt(8)
	v_mfma_f32_32x32x16_bf16 v[32:47], v[162:165], v[216:219], v[32:47]
	s_waitcnt lgkmcnt(6)
	v_mfma_f32_32x32x16_bf16 v[16:31], v[2:5], v[204:207], v[16:31]
	s_waitcnt lgkmcnt(4)
	v_mfma_f32_32x32x16_bf16 v[16:31], v[6:9], v[208:211], v[16:31]
	s_waitcnt lgkmcnt(2)
	v_mfma_f32_32x32x16_bf16 v[16:31], v[10:13], v[212:215], v[16:31]
	s_waitcnt lgkmcnt(0)
	v_mfma_f32_32x32x16_bf16 v[16:31], v[162:165], v[220:223], v[16:31]
	s_barrier
	s_branch .Lafter_bias_0
; template <int D0> __device__ __forceinline__ void pv_one(f32x16& od, int vb, bf16x8 pa0, bf16x8 pa1, bf16x8 pa2, bf16x8 pa3) {
;   const s16x4 l0 = tr_read<v_rd_off(D0, 0, 0)>(vb), h0 = tr_read<v_rd_off(D0, 0, 1)>(vb), l1 = tr_read<v_rd_off(D0, 1, 0)>(vb), h1 = tr_read<v_rd_off(D0, 1, 1)>(vb);
;   const s16x4 l2 = tr_read<v_rd_off(D0, 2, 0)>(vb), h2 = tr_read<v_rd_off(D0, 2, 1)>(vb), l3 = tr_read<v_rd_off(D0, 3, 0)>(vb), h3 = tr_read<v_rd_off(D0, 3, 1)>(vb);
;   asm volatile("s_waitcnt lgkmcnt(0)" ::: "memory"); SBAR();
;     ...
;   od = __builtin_amdgcn_mfma_f32_32x32x16_bf16(pa0, PK(l0, h0), od, 0, 0, 0);
;   od = __builtin_amdgcn_mfma_f32_32x32x16_bf16(pa1, PK(l1, h1), od, 0, 0, 0);
;   od = __builtin_amdgcn_mfma_f32_32x32x16_bf16(pa2, PK(l2, h2), od, 0, 0, 0);
;   od = __builtin_amdgcn_mfma_f32_32x32x16_bf16(pa3, PK(l3, h3), od, 0, 0, 0);
;     ...
; }
; __device__ __forceinline__ void pv_d0(f32x16* o, int vb, bf16x8 pa0, bf16x8 pa1, bf16x8 pa2, bf16x8 pa3) {
;   pv_one<0>(o[0], vb, pa0, pa1, pa2, pa3); pv_one<1>(o[1], vb, pa0, pa1, pa2, pa3); pv_one<2>(o[2], vb, pa0, pa1, pa2, pa3); pv_one<3>(o[3], vb, pa0, pa1, pa2, pa3);
; }
; __device__ __forceinline__ void qkt_c(f32x16& p0, f32x16& p1, const char* Ks, const bf16x8* qr, const f32x16& negm, int r32, int hi) {
; #pragma unroll
;   for (int d0 = 0; d0 < 4; ++d0) { const int cb = (d0 * 16 + hi * 8) * 2;
;     bf16x8 b0 = *reinterpret_cast<const bf16x8*>(Ks + KSWZ(r32, cb));
;     bf16x8 b1 = *reinterpret_cast<const bf16x8*>(Ks + KSWZ(32 + r32, cb));
;     if (d0 == 0) { p0 = __builtin_amdgcn_mfma_f32_32x32x16_bf16(b0, qr[0], negm, 0, 0, 0); p1 = __builtin_amdgcn_mfma_f32_32x32x16_bf16(b1, qr[0], negm, 0, 0, 0); }
;     else { p0 = __builtin_amdgcn_mfma_f32_32x32x16_bf16(b0, qr[d0], p0, 0, 0, 0); p1 = __builtin_amdgcn_mfma_f32_32x32x16_bf16(b1, qr[d0], p1, 0, 0, 0); } }
; }
; template <int R> __device__ __forceinline__ void bias_r(f32x16& p0, f32x16& p1, float dq, float nslope) {
;   constexpr int C0 = (R & 3) + 8 * (R >> 2);
;   float x0, x1, a0 = p0[R], a1 = p1[R];
;   asm("v_sub_f32_e32 %0, %1, %2" : "=v"(x0) : "n"(__builtin_bit_cast(int, (float)C0)), "v"(dq));
;   asm("v_sub_f32_e32 %0, %1, %2" : "=v"(x1) : "n"(__builtin_bit_cast(int, (float)(C0 + 32))), "v"(dq));
;   asm("v_fma_f32 %0, %1, |%2|, %0" : "+v"(a0) : "v"(nslope), "v"(x0));
;   asm("v_fma_f32 %0, %1, |%2|, %0" : "+v"(a1) : "v"(nslope), "v"(x1));
.Lbc_tail_u_0:
	s_waitcnt lgkmcnt(1)
	v_mfma_f32_32x32x16_bf16 v[114:129], v[220:223], v[138:141], v[114:129]
	s_waitcnt lgkmcnt(0)
	v_mfma_f32_32x32x16_bf16 v[114:129], v[212:215], v[142:145], v[114:129]
	s_nop 8
	s_barrier
	s_branch .Lafter_bias_0
.Lbc_mix_0:
	s_waitcnt lgkmcnt(2)
	v_mfma_f32_32x32x16_bf16 v[98:113], v[114:117], v[130:133], v[82:97]
	ds_read_b128 v[220:223], v198 offset:32768
	s_waitcnt lgkmcnt(2)
	v_mfma_f32_32x32x16_bf16 v[98:113], v[212:215], v[134:137], v[98:113]
	ds_read_b128 v[212:215], v195 offset:40960
	s_waitcnt lgkmcnt(2)
	v_mfma_f32_32x32x16_bf16 v[98:113], v[216:219], v[138:141], v[98:113]
	ds_read_b128 v[216:219], v196 offset:40960
	s_waitcnt lgkmcnt(2)
	v_mfma_f32_32x32x16_bf16 v[98:113], v[220:223], v[142:145], v[98:113]
	ds_read_b128 v[220:223], v197 offset:40960
	s_waitcnt lgkmcnt(2)
	v_mfma_f32_32x32x16_bf16 v[114:129], v[212:215], v[130:133], v[82:97]
	ds_read_b128 v[212:215], v198 offset:40960
	s_waitcnt lgkmcnt(2)
	v_mfma_f32_32x32x16_bf16 v[114:129], v[216:219], v[134:137], v[114:129]
	s_cbranch_vccnz .Lbc_tail_m_0
	ds_read_b64_tr_b16 v[204:205], v194 offset:0
	ds_read_b64_tr_b16 v[206:207], v194 offset:0x800
	ds_read_b64_tr_b16 v[208:209], v194 offset:0x1000
	ds_read_b64_tr_b16 v[210:211], v194 offset:0x1800
	s_waitcnt lgkmcnt(5)
	v_mfma_f32_32x32x16_bf16 v[114:129], v[220:223], v[138:141], v[114:129]
	s_waitcnt lgkmcnt(4)
	v_mfma_f32_32x32x16_bf16 v[114:129], v[212:215], v[142:145], v[114:129]
	ds_read_b64_tr_b16 v[212:213], v194 offset:0x2000
	ds_read_b64_tr_b16 v[214:215], v194 offset:0x2800
	ds_read_b64_tr_b16 v[216:217], v194 offset:0x3000
	ds_read_b64_tr_b16 v[218:219], v194 offset:0x3800
	s_waitcnt lgkmcnt(6)
	v_mfma_f32_32x32x16_bf16 v[64:79], v[2:5], v[204:207], v[64:79]
	v_sub_f32_e32 v14, 0, v0
	v_sub_f32_e32 v15, 0x42000000, v0
	v_fma_f32 v98, v81, |v14|, v98
	v_sub_f32_e32 v14, 0x3f800000, v0
	ds_read_b64_tr_b16 v[204:205], v194 offset:0x200
	ds_read_b64_tr_b16 v[206:207], v194 offset:0xa00
	s_waitcnt lgkmcnt(6)
	v_mfma_f32_32x32x16_bf16 v[64:79], v[6:9], v[208:211], v[64:79]
	v_fma_f32 v114, v81, |v15|, v114
	v_sub_f32_e32 v15, 0x42040000, v0
	v_fma_f32 v99, v81, |v14|, v99
	v_sub_f32_e32 v14, 0x40000000, v0
	ds_read_b64_tr_b16 v[208:209], v194 offset:0x1200
	ds_read_b64_tr_b16 v[210:211], v194 offset:0x1a00
	s_waitcnt lgkmcnt(6)
	v_mfma_f32_32x32x16_bf16 v[64:79], v[10:13], v[212:215], v[64:79]
	v_fma_f32 v115, v81, |v15|, v115
	v_sub_f32_e32 v15, 0x42080000, v0
	v_fma_f32 v100, v81, |v14|, v100
	v_sub_f32_e32 v14, 0x40400000, v0
	ds_read_b64_tr_b16 v[212:213], v194 offset:0x2200
	ds_read_b64_tr_b16 v[214:215], v194 offset:0x2a00
	ds_read_b64_tr_b16 v[220:221], v194 offset:0x3200
	ds_read_b64_tr_b16 v[222:223], v194 offset:0x3a00
	s_waitcnt lgkmcnt(8)
	v_mfma_f32_32x32x16_bf16 v[64:79], v[162:165], v[216:219], v[64:79]
	v_fma_f32 v116, v81, |v15|, v116
	v_sub_f32_e32 v15, 0x420c0000, v0
	v_fma_f32 v101, v81, |v14|, v101
	v_sub_f32_e32 v14, 0x41000000, v0
	s_waitcnt lgkmcnt(6)
	v_mfma_f32_32x32x16_bf16 v[48:63], v[2:5], v[204:207], v[48:63]
	v_fma_f32 v117, v81, |v15|, v117
	v_sub_f32_e32 v15, 0x42200000, v0
	v_fma_f32 v102, v81, |v14|, v102
	v_sub_f32_e32 v14, 0x41100000, v0
	ds_read_b64_tr_b16 v[204:205], v194 offset:0x400
	ds_read_b64_tr_b16 v[206:207], v194 offset:0xc00
	s_waitcnt lgkmcnt(6)
	v_mfma_f32_32x32x16_bf16 v[48:63], v[6:9], v[208:211], v[48:63]
	v_fma_f32 v118, v81, |v15|, v118
	v_sub_f32_e32 v15, 0x42240000, v0
	v_fma_f32 v103, v81, |v14|, v103
	v_sub_f32_e32 v14, 0x41200000, v0
	ds_read_b64_tr_b16 v[208:209], v194 offset:0x1400
	ds_read_b64_tr_b16 v[210:211], v194 offset:0x1c00
	s_waitcnt lgkmcnt(6)
	v_mfma_f32_32x32x16_bf16 v[48:63], v[10:13], v[212:215], v[48:63]
	v_fma_f32 v119, v81, |v15|, v119
	v_sub_f32_e32 v15, 0x42280000, v0
	v_fma_f32 v104, v81, |v14|, v104
	v_sub_f32_e32 v14, 0x41300000, v0
	ds_read_b64_tr_b16 v[212:213], v194 offset:0x2400
	ds_read_b64_tr_b16 v[214:215], v194 offset:0x2c00
	ds_read_b64_tr_b16 v[216:217], v194 offset:0x3400
	ds_read_b64_tr_b16 v[218:219], v194 offset:0x3c00
	s_waitcnt lgkmcnt(8)
	v_mfma_f32_32x32x16_bf16 v[48:63], v[162:165], v[220:223], v[48:63]
	v_fma_f32 v120, v81, |v15|, v120
	v_sub_f32_e32 v15, 0x422c0000, v0
	v_fma_f32 v105, v81, |v14|, v105
	v_sub_f32_e32 v14, 0x41800000, v0
	s_waitcnt lgkmcnt(6)
	v_mfma_f32_32x32x16_bf16 v[32:47], v[2:5], v[204:207], v[32:47]
	v_fma_f32 v121, v81, |v15|, v121
	v_sub_f32_e32 v15, 0x42400000, v0
	v_fma_f32 v106, v81, |v14|, v106
	v_sub_f32_e32 v14, 0x41880000, v0
	ds_read_b64_tr_b16 v[204:205], v194 offset:0x600
	ds_read_b64_tr_b16 v[206:207], v194 offset:0xe00
	s_waitcnt lgkmcnt(6)
	v_mfma_f32_32x32x16_bf16 v[32:47], v[6:9], v[208:211], v[32:47]
	v_fma_f32 v122, v81, |v15|, v122
	v_sub_f32_e32 v15, 0x42440000, v0
	v_fma_f32 v107, v81, |v14|, v107
	v_sub_f32_e32 v14, 0x41900000, v0
	ds_read_b64_tr_b16 v[208:209], v194 offset:0x1600
	ds_read_b64_tr_b16 v[210:211], v194 offset:0x1e00
	s_waitcnt lgkmcnt(6)
	v_mfma_f32_32x32x16_bf16 v[32:47], v[10:13], v[212:215], v[32:47]
	v_fma_f32 v123, v81, |v15|, v123
	v_sub_f32_e32 v15, 0x42480000, v0
	v_fma_f32 v108, v81, |v14|, v108
	v_sub_f32_e32 v14, 0x41980000, v0
	ds_read_b64_tr_b16 v[212:213], v194 offset:0x2600
	ds_read_b64_tr_b16 v[214:215], v194 offset:0x2e00
	ds_read_b64_tr_b16 v[220:221], v194 offset:0x3600
	ds_read_b64_tr_b16 v[222:223], v194 offset:0x3e00
	s_waitcnt lgkmcnt(8)
	v_mfma_f32_32x32x16_bf16 v[32:47], v[162:165], v[216:219], v[32:47]
	v_fma_f32 v124, v81, |v15|, v124
	v_sub_f32_e32 v15, 0x424c0000, v0
	v_fma_f32 v109, v81, |v14|, v109
	v_sub_f32_e32 v14, 0x41c00000, v0
	s_waitcnt lgkmcnt(6)
	v_mfma_f32_32x32x16_bf16 v[16:31], v[2:5], v[204:207], v[16:31]
	v_fma_f32 v125, v81, |v15|, v125
	v_sub_f32_e32 v15, 0x42600000, v0
	v_fma_f32 v110, v81, |v14|, v110
	v_sub_f32_e32 v14, 0x41c80000, v0
	s_waitcnt lgkmcnt(4)
	v_mfma_f32_32x32x16_bf16 v[16:31], v[6:9], v[208:211], v[16:31]
	v_fma_f32 v126, v81, |v15|, v126
	v_sub_f32_e32 v15, 0x42640000, v0
	v_fma_f32 v111, v81, |v14|, v111
	v_sub_f32_e32 v14, 0x41d00000, v0
	s_waitcnt lgkmcnt(2)
	v_mfma_f32_32x32x16_bf16 v[16:31], v[10:13], v[212:215], v[16:31]
	v_fma_f32 v127, v81, |v15|, v127
	v_sub_f32_e32 v15, 0x42680000, v0
	v_fma_f32 v112, v81, |v14|, v112
	v_sub_f32_e32 v14, 0x41d80000, v0
	s_waitcnt lgkmcnt(0)
	v_mfma_f32_32x32x16_bf16 v[16:31], v[162:165], v[220:223], v[16:31]
	v_sub_f32_e32 v0, 0x426c0000, v0
	v_fma_f32 v128, v81, |v15|, v128
	v_fma_f32 v113, v81, |v14|, v113
	v_fma_f32 v129, v81, |v0|, v129
	s_barrier
	s_branch .Lafter_bias_0
; template <int R> __device__ __forceinline__ void bias_r(f32x16& p0, f32x16& p1, float dq, float nslope) {
;   constexpr int C0 = (R & 3) + 8 * (R >> 2);
;   float x0, x1, a0 = p0[R], a1 = p1[R];
;   asm("v_sub_f32_e32 %0, %1, %2" : "=v"(x0) : "n"(__builtin_bit_cast(int, (float)C0)), "v"(dq));
;   asm("v_sub_f32_e32 %0, %1, %2" : "=v"(x1) : "n"(__builtin_bit_cast(int, (float)(C0 + 32))), "v"(dq));
;   asm("v_fma_f32 %0, %1, |%2|, %0" : "+v"(a0) : "v"(nslope), "v"(x0));
;   asm("v_fma_f32 %0, %1, |%2|, %0" : "+v"(a1) : "v"(nslope), "v"(x1));
;   p0[R] = a0; p1[R] = a1;
;   if constexpr (R < 15) bias_r<R + 1>(p0, p1, dq, nslope);
; }
.Lbc_tail_m_0:
	s_waitcnt lgkmcnt(1)
	v_mfma_f32_32x32x16_bf16 v[114:129], v[220:223], v[138:141], v[114:129]
	s_waitcnt lgkmcnt(0)
	v_mfma_f32_32x32x16_bf16 v[114:129], v[212:215], v[142:145], v[114:129]
	s_nop 7
	s_barrier
	v_sub_f32_e32 v14, 0, v0
	v_sub_f32_e32 v15, 0x42000000, v0
	v_fma_f32 v98, v81, |v14|, v98
	v_sub_f32_e32 v14, 0x3f800000, v0
	v_fma_f32 v114, v81, |v15|, v114
	v_sub_f32_e32 v15, 0x42040000, v0
	v_fma_f32 v99, v81, |v14|, v99
	v_sub_f32_e32 v14, 0x40000000, v0
	v_fma_f32 v115, v81, |v15|, v115
	v_sub_f32_e32 v15, 0x42080000, v0
	v_fma_f32 v100, v81, |v14|, v100
	v_sub_f32_e32 v14, 0x40400000, v0
	v_fma_f32 v116, v81, |v15|, v116
	v_sub_f32_e32 v15, 0x420c0000, v0
	v_fma_f32 v101, v81, |v14|, v101
	v_sub_f32_e32 v14, 0x41000000, v0
	v_fma_f32 v117, v81, |v15|, v117
	v_sub_f32_e32 v15, 0x42200000, v0
	v_fma_f32 v102, v81, |v14|, v102
	v_sub_f32_e32 v14, 0x41100000, v0
	v_fma_f32 v118, v81, |v15|, v118
	v_sub_f32_e32 v15, 0x42240000, v0
	v_fma_f32 v103, v81, |v14|, v103
	v_sub_f32_e32 v14, 0x41200000, v0
	v_fma_f32 v119, v81, |v15|, v119
	v_sub_f32_e32 v15, 0x42280000, v0
	v_fma_f32 v104, v81, |v14|, v104
	v_sub_f32_e32 v14, 0x41300000, v0
	v_fma_f32 v120, v81, |v15|, v120
	v_sub_f32_e32 v15, 0x422c0000, v0
	v_fma_f32 v105, v81, |v14|, v105
	v_sub_f32_e32 v14, 0x41800000, v0
	v_fma_f32 v121, v81, |v15|, v121
	v_sub_f32_e32 v15, 0x42400000, v0
	v_fma_f32 v106, v81, |v14|, v106
	v_sub_f32_e32 v14, 0x41880000, v0
	v_fma_f32 v122, v81, |v15|, v122
	v_sub_f32_e32 v15, 0x42440000, v0
	v_fma_f32 v107, v81, |v14|, v107
	v_sub_f32_e32 v14, 0x41900000, v0
	v_fma_f32 v123, v81, |v15|, v123
	v_sub_f32_e32 v15, 0x42480000, v0
	v_fma_f32 v108, v81, |v14|, v108
	v_sub_f32_e32 v14, 0x41980000, v0
	v_fma_f32 v124, v81, |v15|, v124
	v_sub_f32_e32 v15, 0x424c0000, v0
	v_fma_f32 v109, v81, |v14|, v109
	v_sub_f32_e32 v14, 0x41c00000, v0
	v_fma_f32 v125, v81, |v15|, v125
	v_sub_f32_e32 v15, 0x42600000, v0
	v_fma_f32 v110, v81, |v14|, v110
	v_sub_f32_e32 v14, 0x41c80000, v0
	v_fma_f32 v126, v81, |v15|, v126
	v_sub_f32_e32 v15, 0x42640000, v0
	v_fma_f32 v111, v81, |v14|, v111
	v_sub_f32_e32 v14, 0x41d00000, v0
	v_fma_f32 v127, v81, |v15|, v127
	v_sub_f32_e32 v15, 0x42680000, v0
	v_fma_f32 v112, v81, |v14|, v112
	v_sub_f32_e32 v14, 0x41d80000, v0
	v_sub_f32_e32 v0, 0x426c0000, v0
	v_fma_f32 v128, v81, |v15|, v128
	v_fma_f32 v113, v81, |v14|, v113
	v_fma_f32 v129, v81, |v0|, v129

; __device__ __forceinline__ void qkt_c(f32x16& p0, f32x16& p1, const char* Ks, const bf16x8* qr, const f32x16& negm, int r32, int hi) {
; #pragma unroll
;   for (int d0 = 0; d0 < 4; ++d0) { const int cb = (d0 * 16 + hi * 8) * 2;
;     bf16x8 b0 = *reinterpret_cast<const bf16x8*>(Ks + KSWZ(r32, cb));
;     bf16x8 b1 = *reinterpret_cast<const bf16x8*>(Ks + KSWZ(32 + r32, cb));
;     if (d0 == 0) { p0 = __builtin_amdgcn_mfma_f32_32x32x16_bf16(b0, qr[0], negm, 0, 0, 0); p1 = __builtin_amdgcn_mfma_f32_32x32x16_bf16(b1, qr[0], negm, 0, 0, 0); }
;     else { p0 = __builtin_amdgcn_mfma_f32_32x32x16_bf16(b0, qr[d0], p0, 0, 0, 0); p1 = __builtin_amdgcn_mfma_f32_32x32x16_bf16(b1, qr[d0], p1, 0, 0, 0); } }
; }
; template <int R> __device__ __forceinline__ void bias_r(f32x16& p0, f32x16& p1, float dq, float nslope) {
;   constexpr int C0 = (R & 3) + 8 * (R >> 2);
;   float x0, x1, a0 = p0[R], a1 = p1[R];
;   asm("v_sub_f32_e32 %0, %1, %2" : "=v"(x0) : "n"(__builtin_bit_cast(int, (float)C0)), "v"(dq));
;   asm("v_sub_f32_e32 %0, %1, %2" : "=v"(x1) : "n"(__builtin_bit_cast(int, (float)(C0 + 32))), "v"(dq));
;   asm("v_fma_f32 %0, %1, |%2|, %0" : "+v"(a0) : "v"(nslope), "v"(x0));
;   asm("v_fma_f32 %0, %1, |%2|, %0" : "+v"(a1) : "v"(nslope), "v"(x1));
;   p0[R] = a0; p1[R] = a1;
;   if constexpr (R < 15) bias_r<R + 1>(p0, p1, dq, nslope);
; }
.LBB0_379:
	s_waitcnt lgkmcnt(0)
	s_barrier
	ds_read_b128 v[114:117], v195 offset:49152
	ds_read_b128 v[212:215], v196 offset:49152
	ds_read_b128 v[216:219], v197 offset:49152
	s_andn2_b64 vcc, exec, s[14:15]
	s_add_i32 s46, s47, -1
	s_add_i32 s72, s72, 1
	s_add_i32 s14, s39, -1
	s_cmp_lt_i32 s46, s23
	s_cselect_b32 s14, s72, s14
	s_lshl_b32 s74, s14, 1
	s_sub_i32 s74, s74, s99
	s_add_i32 s75, s74, 1
	s_lshl_b32 s14, s14, 6
	v_cvt_f32_i32_e32 v0, s14
	v_sub_f32_e32 v0, v192, v0
	s_cmp_lt_u32 s75, 2
	s_cbranch_scc1 .Lbc_mix_1
	s_and_b32 s75, s74, 0x80000000
	v_xor_b32_e32 v14, s75, v81
	v_fma_f32 v15, -v14, v0, v82
	v_fmamk_f32 v240, v14, 0x00000000, v15
	v_fmamk_f32 v241, v14, 0x3f800000, v15
	v_fmamk_f32 v242, v14, 0x40000000, v15
	v_fmamk_f32 v243, v14, 0x40400000, v15
	v_fmamk_f32 v244, v14, 0x41000000, v15
	v_fmamk_f32 v245, v14, 0x41100000, v15
	v_fmamk_f32 v246, v14, 0x41200000, v15
	v_fmamk_f32 v247, v14, 0x41300000, v15
	v_fmamk_f32 v248, v14, 0x41800000, v15
	v_fmamk_f32 v249, v14, 0x41880000, v15
	v_fmamk_f32 v250, v14, 0x41900000, v15
	v_fmamk_f32 v251, v14, 0x41980000, v15
	v_fmamk_f32 v252, v14, 0x41c00000, v15
	v_fmamk_f32 v253, v14, 0x41c80000, v15
	v_fmamk_f32 v254, v14, 0x41d00000, v15
	v_fmamk_f32 v255, v14, 0x41d80000, v15
	s_nop 1
	s_waitcnt lgkmcnt(2)
	v_mfma_f32_32x32x16_bf16 v[98:113], v[114:117], v[130:133], v[240:255]
	ds_read_b128 v[220:223], v198 offset:49152
	s_waitcnt lgkmcnt(2)
	v_mfma_f32_32x32x16_bf16 v[98:113], v[212:215], v[134:137], v[98:113]
	ds_read_b128 v[212:215], v195 offset:57344
	s_waitcnt lgkmcnt(2)
	v_mfma_f32_32x32x16_bf16 v[98:113], v[216:219], v[138:141], v[98:113]
	ds_read_b128 v[216:219], v196 offset:57344
	v_fmamk_f32 v240, v14, 0x42000000, v15
	v_fmamk_f32 v241, v14, 0x42040000, v15
	v_fmamk_f32 v242, v14, 0x42080000, v15
	v_fmamk_f32 v243, v14, 0x420c0000, v15
	v_fmamk_f32 v244, v14, 0x42200000, v15
	v_fmamk_f32 v245, v14, 0x42240000, v15
	v_fmamk_f32 v246, v14, 0x42280000, v15
	v_fmamk_f32 v247, v14, 0x422c0000, v15
	s_waitcnt lgkmcnt(2)
	v_mfma_f32_32x32x16_bf16 v[98:113], v[220:223], v[142:145], v[98:113]
	v_fmamk_f32 v248, v14, 0x42400000, v15
	v_fmamk_f32 v249, v14, 0x42440000, v15
	v_fmamk_f32 v250, v14, 0x42480000, v15
	v_fmamk_f32 v251, v14, 0x424c0000, v15
	v_fmamk_f32 v252, v14, 0x42600000, v15
	v_fmamk_f32 v253, v14, 0x42640000, v15
	v_fmamk_f32 v254, v14, 0x42680000, v15
	v_fmamk_f32 v255, v14, 0x426c0000, v15
	ds_read_b128 v[220:223], v197 offset:57344
	s_waitcnt lgkmcnt(2)
	v_mfma_f32_32x32x16_bf16 v[114:129], v[212:215], v[130:133], v[240:255]
	ds_read_b128 v[212:215], v198 offset:57344
	s_waitcnt lgkmcnt(2)
	v_mfma_f32_32x32x16_bf16 v[114:129], v[216:219], v[134:137], v[114:129]
	s_cbranch_vccnz .Lbc_tail_u_1
	ds_read_b64_tr_b16 v[204:205], v193 offset:0
	ds_read_b64_tr_b16 v[206:207], v193 offset:0x800
	ds_read_b64_tr_b16 v[208:209], v193 offset:0x1000
	ds_read_b64_tr_b16 v[210:211], v193 offset:0x1800
	s_waitcnt lgkmcnt(5)
	v_mfma_f32_32x32x16_bf16 v[114:129], v[220:223], v[138:141], v[114:129]
	s_waitcnt lgkmcnt(4)
	v_mfma_f32_32x32x16_bf16 v[114:129], v[212:215], v[142:145], v[114:129]
	ds_read_b64_tr_b16 v[212:213], v193 offset:0x2000
	ds_read_b64_tr_b16 v[214:215], v193 offset:0x2800
	ds_read_b64_tr_b16 v[216:217], v193 offset:0x3000
	ds_read_b64_tr_b16 v[218:219], v193 offset:0x3800
	s_waitcnt lgkmcnt(6)
	v_mfma_f32_32x32x16_bf16 v[64:79], v[2:5], v[204:207], v[64:79]
	ds_read_b64_tr_b16 v[204:205], v193 offset:0x200
	ds_read_b64_tr_b16 v[206:207], v193 offset:0xa00
	s_waitcnt lgkmcnt(6)
	v_mfma_f32_32x32x16_bf16 v[64:79], v[6:9], v[208:211], v[64:79]
	ds_read_b64_tr_b16 v[208:209], v193 offset:0x1200
	ds_read_b64_tr_b16 v[210:211], v193 offset:0x1a00
	s_waitcnt lgkmcnt(6)
	v_mfma_f32_32x32x16_bf16 v[64:79], v[10:13], v[212:215], v[64:79]
	ds_read_b64_tr_b16 v[212:213], v193 offset:0x2200
	ds_read_b64_tr_b16 v[214:215], v193 offset:0x2a00
	ds_read_b64_tr_b16 v[220:221], v193 offset:0x3200
	ds_read_b64_tr_b16 v[222:223], v193 offset:0x3a00
	s_waitcnt lgkmcnt(8)
	v_mfma_f32_32x32x16_bf16 v[64:79], v[162:165], v[216:219], v[64:79]
	s_waitcnt lgkmcnt(6)
	v_mfma_f32_32x32x16_bf16 v[48:63], v[2:5], v[204:207], v[48:63]
	ds_read_b64_tr_b16 v[204:205], v193 offset:0x400
	ds_read_b64_tr_b16 v[206:207], v193 offset:0xc00
	s_waitcnt lgkmcnt(6)
	v_mfma_f32_32x32x16_bf16 v[48:63], v[6:9], v[208:211], v[48:63]
	ds_read_b64_tr_b16 v[208:209], v193 offset:0x1400
	ds_read_b64_tr_b16 v[210:211], v193 offset:0x1c00
	s_waitcnt lgkmcnt(6)
	v_mfma_f32_32x32x16_bf16 v[48:63], v[10:13], v[212:215], v[48:63]
	ds_read_b64_tr_b16 v[212:213], v193 offset:0x2400
	ds_read_b64_tr_b16 v[214:215], v193 offset:0x2c00
	ds_read_b64_tr_b16 v[216:217], v193 offset:0x3400
	ds_read_b64_tr_b16 v[218:219], v193 offset:0x3c00
	s_waitcnt lgkmcnt(8)
	v_mfma_f32_32x32x16_bf16 v[48:63], v[162:165], v[220:223], v[48:63]
	s_waitcnt lgkmcnt(6)
	v_mfma_f32_32x32x16_bf16 v[32:47], v[2:5], v[204:207], v[32:47]
	ds_read_b64_tr_b16 v[204:205], v193 offset:0x600
	ds_read_b64_tr_b16 v[206:207], v193 offset:0xe00
	s_waitcnt lgkmcnt(6)
	v_mfma_f32_32x32x16_bf16 v[32:47], v[6:9], v[208:211], v[32:47]
	ds_read_b64_tr_b16 v[208:209], v193 offset:0x1600
	ds_read_b64_tr_b16 v[210:211], v193 offset:0x1e00
	s_waitcnt lgkmcnt(6)
	v_mfma_f32_32x32x16_bf16 v[32:47], v[10:13], v[212:215], v[32:47]
	ds_read_b64_tr_b16 v[212:213], v193 offset:0x2600
	ds_read_b64_tr_b16 v[214:215], v193 offset:0x2e00
	ds_read_b64_tr_b16 v[220:221], v193 offset:0x3600
	ds_read_b64_tr_b16 v[222:223], v193 offset:0x3e00
	s_waitcnt lgkmcnt(8)
	v_mfma_f32_32x32x16_bf16 v[32:47], v[162:165], v[216:219], v[32:47]
	s_waitcnt lgkmcnt(6)
	v_mfma_f32_32x32x16_bf16 v[16:31], v[2:5], v[204:207], v[16:31]
	s_waitcnt lgkmcnt(4)
	v_mfma_f32_32x32x16_bf16 v[16:31], v[6:9], v[208:211], v[16:31]
	s_waitcnt lgkmcnt(2)
	v_mfma_f32_32x32x16_bf16 v[16:31], v[10:13], v[212:215], v[16:31]
	s_waitcnt lgkmcnt(0)
	v_mfma_f32_32x32x16_bf16 v[16:31], v[162:165], v[220:223], v[16:31]
	s_barrier
	s_branch .Lafter_bias_1

; template <int D0> __device__ __forceinline__ void pv_one(f32x16& od, int vb, bf16x8 pa0, bf16x8 pa1, bf16x8 pa2, bf16x8 pa3) {
;   const s16x4 l0 = tr_read<v_rd_off(D0, 0, 0)>(vb), h0 = tr_read<v_rd_off(D0, 0, 1)>(vb), l1 = tr_read<v_rd_off(D0, 1, 0)>(vb), h1 = tr_read<v_rd_off(D0, 1, 1)>(vb);
;   const s16x4 l2 = tr_read<v_rd_off(D0, 2, 0)>(vb), h2 = tr_read<v_rd_off(D0, 2, 1)>(vb), l3 = tr_read<v_rd_off(D0, 3, 0)>(vb), h3 = tr_read<v_rd_off(D0, 3, 1)>(vb);
;   asm volatile("s_waitcnt lgkmcnt(0)" ::: "memory"); SBAR();
;     ...
;   od = __builtin_amdgcn_mfma_f32_32x32x16_bf16(pa0, PK(l0, h0), od, 0, 0, 0);
;   od = __builtin_amdgcn_mfma_f32_32x32x16_bf16(pa1, PK(l1, h1), od, 0, 0, 0);
;   od = __builtin_amdgcn_mfma_f32_32x32x16_bf16(pa2, PK(l2, h2), od, 0, 0, 0);
;   od = __builtin_amdgcn_mfma_f32_32x32x16_bf16(pa3, PK(l3, h3), od, 0, 0, 0);
;     ...
; }
; __device__ __forceinline__ void pv_d0(f32x16* o, int vb, bf16x8 pa0, bf16x8 pa1, bf16x8 pa2, bf16x8 pa3) {
;   pv_one<0>(o[0], vb, pa0, pa1, pa2, pa3); pv_one<1>(o[1], vb, pa0, pa1, pa2, pa3); pv_one<2>(o[2], vb, pa0, pa1, pa2, pa3); pv_one<3>(o[3], vb, pa0, pa1, pa2, pa3);
; }
; __device__ __forceinline__ void qkt_c(f32x16& p0, f32x16& p1, const char* Ks, const bf16x8* qr, const f32x16& negm, int r32, int hi) {
; #pragma unroll
;   for (int d0 = 0; d0 < 4; ++d0) { const int cb = (d0 * 16 + hi * 8) * 2;
;     bf16x8 b0 = *reinterpret_cast<const bf16x8*>(Ks + KSWZ(r32, cb));
;     bf16x8 b1 = *reinterpret_cast<const bf16x8*>(Ks + KSWZ(32 + r32, cb));
;     if (d0 == 0) { p0 = __builtin_amdgcn_mfma_f32_32x32x16_bf16(b0, qr[0], negm, 0, 0, 0); p1 = __builtin_amdgcn_mfma_f32_32x32x16_bf16(b1, qr[0], negm, 0, 0, 0); }
;     else { p0 = __builtin_amdgcn_mfma_f32_32x32x16_bf16(b0, qr[d0], p0, 0, 0, 0); p1 = __builtin_amdgcn_mfma_f32_32x32x16_bf16(b1, qr[d0], p1, 0, 0, 0); } }
; }
; template <int R> __device__ __forceinline__ void bias_r(f32x16& p0, f32x16& p1, float dq, float nslope) {
;   constexpr int C0 = (R & 3) + 8 * (R >> 2);
;   float x0, x1, a0 = p0[R], a1 = p1[R];
;   asm("v_sub_f32_e32 %0, %1, %2" : "=v"(x0) : "n"(__builtin_bit_cast(int, (float)C0)), "v"(dq));
;   asm("v_sub_f32_e32 %0, %1, %2" : "=v"(x1) : "n"(__builtin_bit_cast(int, (float)(C0 + 32))), "v"(dq));
;   asm("v_fma_f32 %0, %1, |%2|, %0" : "+v"(a0) : "v"(nslope), "v"(x0));
;   asm("v_fma_f32 %0, %1, |%2|, %0" : "+v"(a1) : "v"(nslope), "v"(x1));
.Lbc_mix_1:
	s_waitcnt lgkmcnt(2)
	v_mfma_f32_32x32x16_bf16 v[98:113], v[114:117], v[130:133], v[82:97]
	ds_read_b128 v[220:223], v198 offset:49152
	s_waitcnt lgkmcnt(2)
	v_mfma_f32_32x32x16_bf16 v[98:113], v[212:215], v[134:137], v[98:113]
	ds_read_b128 v[212:215], v195 offset:57344
	s_waitcnt lgkmcnt(2)
	v_mfma_f32_32x32x16_bf16 v[98:113], v[216:219], v[138:141], v[98:113]
	ds_read_b128 v[216:219], v196 offset:57344
	s_waitcnt lgkmcnt(2)
	v_mfma_f32_32x32x16_bf16 v[98:113], v[220:223], v[142:145], v[98:113]
	ds_read_b128 v[220:223], v197 offset:57344
	s_waitcnt lgkmcnt(2)
	v_mfma_f32_32x32x16_bf16 v[114:129], v[212:215], v[130:133], v[82:97]
	ds_read_b128 v[212:215], v198 offset:57344
	s_waitcnt lgkmcnt(2)
	v_mfma_f32_32x32x16_bf16 v[114:129], v[216:219], v[134:137], v[114:129]
	s_cbranch_vccnz .Lbc_tail_m_1
	ds_read_b64_tr_b16 v[204:205], v193 offset:0
	ds_read_b64_tr_b16 v[206:207], v193 offset:0x800
	ds_read_b64_tr_b16 v[208:209], v193 offset:0x1000
	ds_read_b64_tr_b16 v[210:211], v193 offset:0x1800
	s_waitcnt lgkmcnt(5)
	v_mfma_f32_32x32x16_bf16 v[114:129], v[220:223], v[138:141], v[114:129]
	s_waitcnt lgkmcnt(4)
	v_mfma_f32_32x32x16_bf16 v[114:129], v[212:215], v[142:145], v[114:129]
	ds_read_b64_tr_b16 v[212:213], v193 offset:0x2000
	ds_read_b64_tr_b16 v[214:215], v193 offset:0x2800
	ds_read_b64_tr_b16 v[216:217], v193 offset:0x3000
	ds_read_b64_tr_b16 v[218:219], v193 offset:0x3800
	s_waitcnt lgkmcnt(6)
	v_mfma_f32_32x32x16_bf16 v[64:79], v[2:5], v[204:207], v[64:79]
	v_sub_f32_e32 v14, 0, v0
	v_sub_f32_e32 v15, 0x42000000, v0
	v_fma_f32 v98, v81, |v14|, v98
	v_sub_f32_e32 v14, 0x3f800000, v0
	ds_read_b64_tr_b16 v[204:205], v193 offset:0x200
	ds_read_b64_tr_b16 v[206:207], v193 offset:0xa00
	s_waitcnt lgkmcnt(6)
	v_mfma_f32_32x32x16_bf16 v[64:79], v[6:9], v[208:211], v[64:79]
	v_fma_f32 v114, v81, |v15|, v114
	v_sub_f32_e32 v15, 0x42040000, v0
	v_fma_f32 v99, v81, |v14|, v99
	v_sub_f32_e32 v14, 0x40000000, v0
	ds_read_b64_tr_b16 v[208:209], v193 offset:0x1200
	ds_read_b64_tr_b16 v[210:211], v193 offset:0x1a00
	s_waitcnt lgkmcnt(6)
	v_mfma_f32_32x32x16_bf16 v[64:79], v[10:13], v[212:215], v[64:79]
	v_fma_f32 v115, v81, |v15|, v115
	v_sub_f32_e32 v15, 0x42080000, v0
	v_fma_f32 v100, v81, |v14|, v100
	v_sub_f32_e32 v14, 0x40400000, v0
	ds_read_b64_tr_b16 v[212:213], v193 offset:0x2200
	ds_read_b64_tr_b16 v[214:215], v193 offset:0x2a00
	ds_read_b64_tr_b16 v[220:221], v193 offset:0x3200
	ds_read_b64_tr_b16 v[222:223], v193 offset:0x3a00
	s_waitcnt lgkmcnt(8)
	v_mfma_f32_32x32x16_bf16 v[64:79], v[162:165], v[216:219], v[64:79]
	v_fma_f32 v116, v81, |v15|, v116
	v_sub_f32_e32 v15, 0x420c0000, v0
	v_fma_f32 v101, v81, |v14|, v101
	v_sub_f32_e32 v14, 0x41000000, v0
	s_waitcnt lgkmcnt(6)
	v_mfma_f32_32x32x16_bf16 v[48:63], v[2:5], v[204:207], v[48:63]
	v_fma_f32 v117, v81, |v15|, v117
	v_sub_f32_e32 v15, 0x42200000, v0
	v_fma_f32 v102, v81, |v14|, v102
	v_sub_f32_e32 v14, 0x41100000, v0
	ds_read_b64_tr_b16 v[204:205], v193 offset:0x400
	ds_read_b64_tr_b16 v[206:207], v193 offset:0xc00
	s_waitcnt lgkmcnt(6)
	v_mfma_f32_32x32x16_bf16 v[48:63], v[6:9], v[208:211], v[48:63]
	v_fma_f32 v118, v81, |v15|, v118
	v_sub_f32_e32 v15, 0x42240000, v0
	v_fma_f32 v103, v81, |v14|, v103
	v_sub_f32_e32 v14, 0x41200000, v0
	ds_read_b64_tr_b16 v[208:209], v193 offset:0x1400
	ds_read_b64_tr_b16 v[210:211], v193 offset:0x1c00
	s_waitcnt lgkmcnt(6)
	v_mfma_f32_32x32x16_bf16 v[48:63], v[10:13], v[212:215], v[48:63]
	v_fma_f32 v119, v81, |v15|, v119
	v_sub_f32_e32 v15, 0x42280000, v0
	v_fma_f32 v104, v81, |v14|, v104
	v_sub_f32_e32 v14, 0x41300000, v0
	ds_read_b64_tr_b16 v[212:213], v193 offset:0x2400
	ds_read_b64_tr_b16 v[214:215], v193 offset:0x2c00
	ds_read_b64_tr_b16 v[216:217], v193 offset:0x3400
	ds_read_b64_tr_b16 v[218:219], v193 offset:0x3c00
	s_waitcnt lgkmcnt(8)
	v_mfma_f32_32x32x16_bf16 v[48:63], v[162:165], v[220:223], v[48:63]
	v_fma_f32 v120, v81, |v15|, v120
	v_sub_f32_e32 v15, 0x422c0000, v0
	v_fma_f32 v105, v81, |v14|, v105
	v_sub_f32_e32 v14, 0x41800000, v0
	s_waitcnt lgkmcnt(6)
	v_mfma_f32_32x32x16_bf16 v[32:47], v[2:5], v[204:207], v[32:47]
	v_fma_f32 v121, v81, |v15|, v121
	v_sub_f32_e32 v15, 0x42400000, v0
	v_fma_f32 v106, v81, |v14|, v106
	v_sub_f32_e32 v14, 0x41880000, v0
	ds_read_b64_tr_b16 v[204:205], v193 offset:0x600
	ds_read_b64_tr_b16 v[206:207], v193 offset:0xe00
	s_waitcnt lgkmcnt(6)
	v_mfma_f32_32x32x16_bf16 v[32:47], v[6:9], v[208:211], v[32:47]
	v_fma_f32 v122, v81, |v15|, v122
	v_sub_f32_e32 v15, 0x42440000, v0
	v_fma_f32 v107, v81, |v14|, v107
	v_sub_f32_e32 v14, 0x41900000, v0
	ds_read_b64_tr_b16 v[208:209], v193 offset:0x1600
	ds_read_b64_tr_b16 v[210:211], v193 offset:0x1e00
	s_waitcnt lgkmcnt(6)
	v_mfma_f32_32x32x16_bf16 v[32:47], v[10:13], v[212:215], v[32:47]
	v_fma_f32 v123, v81, |v15|, v123
	v_sub_f32_e32 v15, 0x42480000, v0
	v_fma_f32 v108, v81, |v14|, v108
	v_sub_f32_e32 v14, 0x41980000, v0
	ds_read_b64_tr_b16 v[212:213], v193 offset:0x2600
	ds_read_b64_tr_b16 v[214:215], v193 offset:0x2e00
	ds_read_b64_tr_b16 v[220:221], v193 offset:0x3600
	ds_read_b64_tr_b16 v[222:223], v193 offset:0x3e00
	s_waitcnt lgkmcnt(8)
	v_mfma_f32_32x32x16_bf16 v[32:47], v[162:165], v[216:219], v[32:47]
	v_fma_f32 v124, v81, |v15|, v124
	v_sub_f32_e32 v15, 0x424c0000, v0
	v_fma_f32 v109, v81, |v14|, v109
	v_sub_f32_e32 v14, 0x41c00000, v0
	s_waitcnt lgkmcnt(6)
	v_mfma_f32_32x32x16_bf16 v[16:31], v[2:5], v[204:207], v[16:31]
	v_fma_f32 v125, v81, |v15|, v125
	v_sub_f32_e32 v15, 0x42600000, v0
	v_fma_f32 v110, v81, |v14|, v110
	v_sub_f32_e32 v14, 0x41c80000, v0
	s_waitcnt lgkmcnt(4)
	v_mfma_f32_32x32x16_bf16 v[16:31], v[6:9], v[208:211], v[16:31]
	v_fma_f32 v126, v81, |v15|, v126
	v_sub_f32_e32 v15, 0x42640000, v0
	v_fma_f32 v111, v81, |v14|, v111
	v_sub_f32_e32 v14, 0x41d00000, v0
	s_waitcnt lgkmcnt(2)
	v_mfma_f32_32x32x16_bf16 v[16:31], v[10:13], v[212:215], v[16:31]
	v_fma_f32 v127, v81, |v15|, v127
	v_sub_f32_e32 v15, 0x42680000, v0
	v_fma_f32 v112, v81, |v14|, v112
	v_sub_f32_e32 v14, 0x41d80000, v0
	s_waitcnt lgkmcnt(0)
	v_mfma_f32_32x32x16_bf16 v[16:31], v[162:165], v[220:223], v[16:31]
	v_sub_f32_e32 v0, 0x426c0000, v0
	v_fma_f32 v128, v81, |v15|, v128
	v_fma_f32 v113, v81, |v14|, v113
	v_fma_f32 v129, v81, |v0|, v129
	s_barrier
	s_branch .Lafter_bias_1

; __global__ void __launch_bounds__(NWAVES * 64) mega_fwd(Args args) {
	.amdhsa_kernel _Z8mega_fwd4Args
		.amdhsa_group_segment_fixed_size 0
		.amdhsa_private_segment_fixed_size 0
		.amdhsa_kernarg_size 424
		.amdhsa_user_sgpr_count 2
		.amdhsa_user_sgpr_dispatch_ptr 0
		.amdhsa_user_sgpr_queue_ptr 0
		.amdhsa_user_sgpr_kernarg_segment_ptr 1
		.amdhsa_user_sgpr_dispatch_id 0
		.amdhsa_user_sgpr_kernarg_preload_length 0
		.amdhsa_user_sgpr_kernarg_preload_offset 0
		.amdhsa_user_sgpr_private_segment_size 0
		.amdhsa_uses_dynamic_stack 0
		.amdhsa_enable_private_segment 0
		.amdhsa_system_sgpr_workgroup_id_x 1
		.amdhsa_system_sgpr_workgroup_id_y 0
		.amdhsa_system_sgpr_workgroup_id_z 0
		.amdhsa_system_sgpr_workgroup_info 0
		.amdhsa_system_vgpr_workitem_id 2
		.amdhsa_next_free_vgpr 256
		.amdhsa_next_free_sgpr 102
		.amdhsa_accum_offset 256
		.amdhsa_reserve_vcc 1
		.amdhsa_float_round_mode_32 0
		.amdhsa_float_round_mode_16_64 0
		.amdhsa_float_denorm_mode_32 3
		.amdhsa_float_denorm_mode_16_64 3
		.amdhsa_dx10_clamp 1
		.amdhsa_ieee_mode 1
		.amdhsa_fp16_overflow 0
		.amdhsa_tg_split 0
		.amdhsa_exception_fp_ieee_invalid_op 0
		.amdhsa_exception_fp_denorm_src 0
		.amdhsa_exception_fp_ieee_div_zero 0
		.amdhsa_exception_fp_ieee_overflow 0
		.amdhsa_exception_fp_ieee_underflow 0
		.amdhsa_exception_fp_ieee_inexact 0
		.amdhsa_exception_int_div_zero 0
	.end_amdhsa_kernel

; __global__ void __launch_bounds__(NWAVES * 64) mega_fwd(Args args) {
amdhsa.kernels:
  - .agpr_count:     0
    .args:
      - .offset:         0
        .size:           168
        .value_kind:     by_value
      - .offset:         168
        .size:           4
        .value_kind:     hidden_block_count_x
      - .offset:         172
        .size:           4
        .value_kind:     hidden_block_count_y
      - .offset:         176
        .size:           4
        .value_kind:     hidden_block_count_z
      - .offset:         180
        .size:           2
        .value_kind:     hidden_group_size_x
      - .offset:         182
        .size:           2
        .value_kind:     hidden_group_size_y
      - .offset:         184
        .size:           2
        .value_kind:     hidden_group_size_z
      - .offset:         186
        .size:           2
        .value_kind:     hidden_remainder_x
      - .offset:         188
        .size:           2
        .value_kind:     hidden_remainder_y
      - .offset:         190
        .size:           2
        .value_kind:     hidden_remainder_z
      - .offset:         208
        .size:           8
        .value_kind:     hidden_global_offset_x
      - .offset:         216
        .size:           8
        .value_kind:     hidden_global_offset_y
      - .offset:         224
        .size:           8
        .value_kind:     hidden_global_offset_z
      - .offset:         232
        .size:           2
        .value_kind:     hidden_grid_dims
      - .offset:         256
        .size:           8
        .value_kind:     hidden_multigrid_sync_arg
      - .offset:         288
        .size:           4
        .value_kind:     hidden_dynamic_lds_size
    .group_segment_fixed_size: 0
    .kernarg_segment_align: 8
    .kernarg_segment_size: 424
    .language:       OpenCL C
    .language_version:
      - 2
      - 0
    .max_flat_workgroup_size: 512
    .name:           _Z8mega_fwd4Args
    .private_segment_fixed_size: 0
    .sgpr_count:     108
    .sgpr_spill_count: 22
    .symbol:         _Z8mega_fwd4Args.kd
    .uniform_work_group_size: 1
    .uses_dynamic_stack: false
    .vgpr_count:     256
    .vgpr_spill_count: 0
    .wavefront_size: 64
